# GEMM phases: one static s_setprio 1 for waves 4-7 (second-dispatched half), reset at phase exit
# speedup vs baseline: 1.0069x; 1.0069x over previous
; DI int tidx() { int t = threadIdx.x; asm volatile("" : "+v"(t)); return t; }
; template <int EPI>
; DI bool tile_coords(int j, int mpx, int& m0, int& n0) {
;     ...
;     if (q >= mpx * 4) return false;
;     m0 = (x * mpx + (q >> 2)) * 256;
;     n0 = (q & 3) * 256;
;   }
;   return true;
; }
; template <int EPI>
; DI void gemm_phase(const P& p, int l, const u16* __restrict__ A, const u16* __restrict__ Bt, int mpx, char* lds) {
;   const int tid = tidx();
;   int t = 0;
;   int m0, n0;
;   if (!tile_coords<EPI>(t, mpx, m0, n0)) return;
.LBB0_66:
	s_andn2_b64 vcc, exec, s[0:1]
	s_cbranch_vccnz .LBB0_73
	s_cmp_lt_u32 s23, 4
	s_cselect_b64 s[0:1], -1, 0
	s_and_b64 s[26:27], s[0:1], exec
	s_cselect_b32 s2, 18, 16
	s_lshl_b32 s25, s2, 2
	s_cmp_lt_u32 s84, s25
	v_mov_b32_e32 v0, v195
	s_cbranch_scc0 .LBB0_73
	v_readfirstlane_b32 s100, v195
	s_cmp_lt_u32 s100, 0x100
	s_cbranch_scc1 .Lprio_out
	s_setprio 1
.Lprio_out:
	s_cmp_lg_u32 s50, 0
	s_cbranch_scc1 .Ldephase_out_done
	s_cmp_lt_u32 s84, 8
	s_cbranch_scc1 .Ldephase_out_done
	s_sleep 127
	s_sleep 127
	s_sleep 127
	s_sleep 127
	s_sleep 127

; DI int tidx() { int t = threadIdx.x; asm volatile("" : "+v"(t)); return t; }
; template <int EPI>
; DI void gemm_phase(const P& p, int l, const u16* __restrict__ A, const u16* __restrict__ Bt, int mpx, char* lds) {
;   const int tid = tidx();
;   int t = 0;
;   int m0, n0;
;   if (!tile_coords<EPI>(t, mpx, m0, n0)) return;
;   const unsigned voffb = (unsigned)(((tid >> 3) * 1024 + (tid & 7) * 8) * 2);
;   const u16* Ag = A + (size_t)m0 * 1024;
;   const u16* Bg = Bt + (size_t)n0 * 1024;
; DI void phase_inproj(const P& p, int l, char* lds) {
;   gemm_phase<0>(p, l, p.H, p.Wt + (size_t)l * NIN * 1024, (MALL / 256) / 8, lds);
.LBB0_73:
	s_setprio 0
	s_mov_b64 s[0:1], 0
.LBB0_74:
	s_andn2_b64 vcc, exec, s[0:1]
	s_cbranch_vccnz .LBB0_941
	s_cmp_lg_u32 s24, 1
	s_mov_b64 s[0:1], -1
	s_cbranch_scc0 .LBB0_812
	v_readlane_b32 s0, v254, 9
	v_readlane_b32 s1, v254, 10
	v_mov_b32_e32 v0, v195
	s_andn2_b64 vcc, exec, s[0:1]
	s_cbranch_vccnz .LBB0_811
	v_readfirstlane_b32 s100, v195
	s_cmp_lt_u32 s100, 0x100
	s_cbranch_scc1 .Lprio_in
	s_setprio 1
.Lprio_in:
	s_cmp_lg_u32 s50, 0
	s_cbranch_scc1 .Ldephase_in_done
	s_cmp_lt_u32 s84, 14
	s_cbranch_scc1 .Ldephase_in_done
	s_sleep 127
	s_sleep 127
	s_sleep 127
	s_sleep 127
